# PAB EpiMerge epilogue de-serialised: gate loads issued ahead in a ring of 6 row groups, stores at the end (same arithmetic)
# baseline (speedup 1.0000x reference)
; __device__ __forceinline__ unsigned cvt_pk_bf16(float lo, float hi) { unsigned r; asm volatile("v_cvt_pk_bf16_f32 %0, %1, %2" : "=v"(r) : "v"(lo), "v"(hi)); return r; }
; __device__ __forceinline__ float bflo(unsigned w) { return __uint_as_float(w << 16); }
; __device__ __forceinline__ float bfhi(unsigned w) { return __uint_as_float(w & 0xffff0000u); }
;     __device__ __forceinline__ void operator()(const f32x4 (&acc)[2][2][4][2], const Unit& u, int wr, int wc, int fr, int fq) const {
;         const int row0 = u.pm * BM + wr * 64 + fr, col0 = u.pn * HALF + wc * 32 + 8 * fq;
; #pragma unroll
;         for (int ai = 0; ai < 2; ++ai)
; #pragma unroll
;             for (int m = 0; m < 4; ++m) {
;                 const int row = row0 + ai * HALF + m * 16;
;                 const u32x4 ga = *(const u32x4*)(GT + (size_t)row * 2048 + col0), gb = *(const u32x4*)(GT + (size_t)row * 2048 + 1024 + col0);
;                 const f32x4 a0 = acc[ai][0][m][0], a1 = acc[ai][0][m][1], b0 = acc[ai][1][m][0], b1 = acc[ai][1][m][1];
;                 u32x4 w;
;                 w.x = cvt_pk_bf16(bflo(ga.x) * a0[0] + bflo(gb.x) * b0[0], bfhi(ga.x) * a0[1] + bfhi(gb.x) * b0[1]);
;                 w.y = cvt_pk_bf16(bflo(ga.y) * a0[2] + bflo(gb.y) * b0[2], bfhi(ga.y) * a0[3] + bfhi(gb.y) * b0[3]);
;                 w.z = cvt_pk_bf16(bflo(ga.z) * a1[0] + bflo(gb.z) * b1[0], bfhi(ga.z) * a1[1] + bfhi(gb.z) * b1[1]);
;                 w.w = cvt_pk_bf16(bflo(ga.w) * a1[2] + bflo(gb.w) * b1[2], bfhi(ga.w) * a1[3] + bfhi(gb.w) * b1[3]);
.LBB0_1050:
	s_andn2_b64 vcc, exec, s[4:5]
	s_mov_b64 s[4:5], -1
	v_lshl_add_u32 v196, s72, 8, v144
	v_lshl_or_b32 v194, s97, 7, v147
	v_ashrrev_i32_e32 v197, 31, v196
	v_ashrrev_i32_e32 v195, 31, v194
	v_lshlrev_b64 v[190:191], 12, v[196:197]
	v_lshlrev_b64 v[194:195], 1, v[194:195]
	v_lshl_add_u64 v[190:191], s[12:13], 0, v[190:191]
	v_lshlrev_b64 v[192:193], 11, v[196:197]
	v_lshl_add_u64 v[190:191], v[190:191], 0, v[194:195]
	v_lshl_add_u64 v[192:193], s[14:15], 0, v[192:193]
	v_lshl_add_u64 v[192:193], v[192:193], 0, v[194:195]
	global_load_dwordx4 v[212:215], v[190:191], off
	global_load_dwordx4 v[216:219], v[190:191], off offset:2048
	s_mov_b64 s[6:7], 0x10000
	v_lshl_add_u64 v[198:199], v[190:191], 0, s[6:7]
	global_load_dwordx4 v[220:223], v[198:199], off
	global_load_dwordx4 v[224:227], v[198:199], off offset:2048
	s_mov_b64 s[6:7], 0x20000
	v_lshl_add_u64 v[248:249], v[190:191], 0, s[6:7]
	global_load_dwordx4 v[228:231], v[248:249], off
	global_load_dwordx4 v[232:235], v[248:249], off offset:2048
	s_mov_b64 s[6:7], 0x30000
	v_lshl_add_u64 v[198:199], v[190:191], 0, s[6:7]
	global_load_dwordx4 v[236:239], v[198:199], off
	global_load_dwordx4 v[240:243], v[198:199], off offset:2048
	s_mov_b64 s[6:7], 0x80000
	v_lshl_add_u64 v[248:249], v[190:191], 0, s[6:7]
	global_load_dwordx4 v[244:247], v[248:249], off
	global_load_dwordx4 v[150:153], v[248:249], off offset:2048
	s_mov_b64 s[6:7], 0x90000
	v_lshl_add_u64 v[198:199], v[190:191], 0, s[6:7]
	global_load_dwordx4 v[154:157], v[198:199], off
	global_load_dwordx4 v[158:161], v[198:199], off offset:2048
	s_waitcnt vmcnt(10)
	v_lshlrev_b32_e32 v162, 16, v212
	v_and_b32_e32 v163, 0xffff0000, v212
	v_lshlrev_b32_e32 v170, 16, v216
	v_and_b32_e32 v171, 0xffff0000, v216
	v_lshlrev_b32_e32 v164, 16, v213
	v_and_b32_e32 v165, 0xffff0000, v213
	v_lshlrev_b32_e32 v172, 16, v217
	v_and_b32_e32 v173, 0xffff0000, v217
	v_lshlrev_b32_e32 v166, 16, v214
	v_and_b32_e32 v167, 0xffff0000, v214
	v_lshlrev_b32_e32 v186, 16, v218
	v_and_b32_e32 v187, 0xffff0000, v218
	v_lshlrev_b32_e32 v168, 16, v215
	v_and_b32_e32 v169, 0xffff0000, v215
	v_lshlrev_b32_e32 v188, 16, v219
	v_and_b32_e32 v189, 0xffff0000, v219
	s_mov_b64 s[6:7], 0xa0000
	v_lshl_add_u64 v[248:249], v[190:191], 0, s[6:7]
	global_load_dwordx4 v[212:215], v[248:249], off
	global_load_dwordx4 v[216:219], v[248:249], off offset:2048
	v_pk_mul_f32 v[72:73], v[72:73], v[162:163]
	v_pk_mul_f32 v[124:125], v[124:125], v[170:171]
	v_pk_mul_f32 v[74:75], v[74:75], v[164:165]
	v_pk_mul_f32 v[126:127], v[126:127], v[172:173]
	v_pk_mul_f32 v[64:65], v[64:65], v[166:167]
	v_pk_mul_f32 v[120:121], v[120:121], v[186:187]
	v_pk_mul_f32 v[66:67], v[66:67], v[168:169]
	v_pk_mul_f32 v[122:123], v[122:123], v[188:189]
	v_pk_add_f32 v[72:73], v[72:73], v[124:125]
	v_pk_add_f32 v[74:75], v[74:75], v[126:127]
	v_pk_add_f32 v[64:65], v[64:65], v[120:121]
	v_pk_add_f32 v[66:67], v[66:67], v[122:123]
	v_cvt_pk_bf16_f32 v124, v72, v73
	v_cvt_pk_bf16_f32 v125, v74, v75
	v_cvt_pk_bf16_f32 v126, v64, v65
	v_cvt_pk_bf16_f32 v127, v66, v67
	s_waitcnt vmcnt(10)
	v_lshlrev_b32_e32 v162, 16, v220
	v_and_b32_e32 v163, 0xffff0000, v220
	v_lshlrev_b32_e32 v170, 16, v224
	v_and_b32_e32 v171, 0xffff0000, v224
	v_lshlrev_b32_e32 v164, 16, v221
	v_and_b32_e32 v165, 0xffff0000, v221
	v_lshlrev_b32_e32 v172, 16, v225
	v_and_b32_e32 v173, 0xffff0000, v225
	v_lshlrev_b32_e32 v166, 16, v222
	v_and_b32_e32 v167, 0xffff0000, v222
	v_lshlrev_b32_e32 v186, 16, v226
	v_and_b32_e32 v187, 0xffff0000, v226
	v_lshlrev_b32_e32 v168, 16, v223
	v_and_b32_e32 v169, 0xffff0000, v223
	v_lshlrev_b32_e32 v188, 16, v227
	v_and_b32_e32 v189, 0xffff0000, v227
	s_mov_b64 s[6:7], 0xb0000
	v_lshl_add_u64 v[198:199], v[190:191], 0, s[6:7]
	global_load_dwordx4 v[220:223], v[198:199], off
	global_load_dwordx4 v[224:227], v[198:199], off offset:2048
	v_pk_mul_f32 v[52:53], v[52:53], v[162:163]
	v_pk_mul_f32 v[116:117], v[116:117], v[170:171]
	v_pk_mul_f32 v[54:55], v[54:55], v[164:165]
	v_pk_mul_f32 v[118:119], v[118:119], v[172:173]
	v_pk_mul_f32 v[48:49], v[48:49], v[166:167]
	v_pk_mul_f32 v[112:113], v[112:113], v[186:187]
	v_pk_mul_f32 v[50:51], v[50:51], v[168:169]
	v_pk_mul_f32 v[114:115], v[114:115], v[188:189]
	v_pk_add_f32 v[52:53], v[52:53], v[116:117]
	v_pk_add_f32 v[54:55], v[54:55], v[118:119]
	v_pk_add_f32 v[48:49], v[48:49], v[112:113]
	v_pk_add_f32 v[50:51], v[50:51], v[114:115]
	v_cvt_pk_bf16_f32 v116, v52, v53
	v_cvt_pk_bf16_f32 v117, v54, v55
	v_cvt_pk_bf16_f32 v118, v48, v49
	v_cvt_pk_bf16_f32 v119, v50, v51
	s_waitcnt vmcnt(10)
	v_lshlrev_b32_e32 v162, 16, v228
	v_and_b32_e32 v163, 0xffff0000, v228
	v_lshlrev_b32_e32 v170, 16, v232
	v_and_b32_e32 v171, 0xffff0000, v232
	v_lshlrev_b32_e32 v164, 16, v229
	v_and_b32_e32 v165, 0xffff0000, v229
	v_lshlrev_b32_e32 v172, 16, v233
	v_and_b32_e32 v173, 0xffff0000, v233
	v_lshlrev_b32_e32 v166, 16, v230
	v_and_b32_e32 v167, 0xffff0000, v230
	v_lshlrev_b32_e32 v186, 16, v234
	v_and_b32_e32 v187, 0xffff0000, v234
	v_lshlrev_b32_e32 v168, 16, v231
	v_and_b32_e32 v169, 0xffff0000, v231
	v_lshlrev_b32_e32 v188, 16, v235
	v_and_b32_e32 v189, 0xffff0000, v235
	v_pk_mul_f32 v[44:45], v[44:45], v[162:163]
	v_pk_mul_f32 v[108:109], v[108:109], v[170:171]
	v_pk_mul_f32 v[46:47], v[46:47], v[164:165]
	v_pk_mul_f32 v[110:111], v[110:111], v[172:173]
	v_pk_mul_f32 v[40:41], v[40:41], v[166:167]
	v_pk_mul_f32 v[104:105], v[104:105], v[186:187]
	v_pk_mul_f32 v[42:43], v[42:43], v[168:169]
	v_pk_mul_f32 v[106:107], v[106:107], v[188:189]
	v_pk_add_f32 v[44:45], v[44:45], v[108:109]
	v_pk_add_f32 v[46:47], v[46:47], v[110:111]
	v_pk_add_f32 v[40:41], v[40:41], v[104:105]
	v_pk_add_f32 v[42:43], v[42:43], v[106:107]
	v_cvt_pk_bf16_f32 v108, v44, v45
	v_cvt_pk_bf16_f32 v109, v46, v47
	v_cvt_pk_bf16_f32 v110, v40, v41
	v_cvt_pk_bf16_f32 v111, v42, v43
	s_waitcnt vmcnt(8)
; __device__ __forceinline__ unsigned cvt_pk_bf16(float lo, float hi) { unsigned r; asm volatile("v_cvt_pk_bf16_f32 %0, %1, %2" : "=v"(r) : "v"(lo), "v"(hi)); return r; }
; __device__ __forceinline__ float bflo(unsigned w) { return __uint_as_float(w << 16); }
; __device__ __forceinline__ float bfhi(unsigned w) { return __uint_as_float(w & 0xffff0000u); }
;     __device__ __forceinline__ void operator()(const f32x4 (&acc)[2][2][4][2], const Unit& u, int wr, int wc, int fr, int fq) const {
;     ...
;                 const f32x4 a0 = acc[ai][0][m][0], a1 = acc[ai][0][m][1], b0 = acc[ai][1][m][0], b1 = acc[ai][1][m][1];
;                 u32x4 w;
;                 w.x = cvt_pk_bf16(bflo(ga.x) * a0[0] + bflo(gb.x) * b0[0], bfhi(ga.x) * a0[1] + bfhi(gb.x) * b0[1]);
;                 w.y = cvt_pk_bf16(bflo(ga.y) * a0[2] + bflo(gb.y) * b0[2], bfhi(ga.y) * a0[3] + bfhi(gb.y) * b0[3]);
;                 w.z = cvt_pk_bf16(bflo(ga.z) * a1[0] + bflo(gb.z) * b1[0], bfhi(ga.z) * a1[1] + bfhi(gb.z) * b1[1]);
;                 w.w = cvt_pk_bf16(bflo(ga.w) * a1[2] + bflo(gb.w) * b1[2], bfhi(ga.w) * a1[3] + bfhi(gb.w) * b1[3]);
	v_lshlrev_b32_e32 v162, 16, v236
	v_and_b32_e32 v163, 0xffff0000, v236
	v_lshlrev_b32_e32 v170, 16, v240
	v_and_b32_e32 v171, 0xffff0000, v240
	v_lshlrev_b32_e32 v164, 16, v237
	v_and_b32_e32 v165, 0xffff0000, v237
	v_lshlrev_b32_e32 v172, 16, v241
	v_and_b32_e32 v173, 0xffff0000, v241
	v_lshlrev_b32_e32 v166, 16, v238
	v_and_b32_e32 v167, 0xffff0000, v238
	v_lshlrev_b32_e32 v186, 16, v242
	v_and_b32_e32 v187, 0xffff0000, v242
	v_lshlrev_b32_e32 v168, 16, v239
	v_and_b32_e32 v169, 0xffff0000, v239
	v_lshlrev_b32_e32 v188, 16, v243
	v_and_b32_e32 v189, 0xffff0000, v243
	v_pk_mul_f32 v[36:37], v[36:37], v[162:163]
	v_pk_mul_f32 v[100:101], v[100:101], v[170:171]
	v_pk_mul_f32 v[38:39], v[38:39], v[164:165]
	v_pk_mul_f32 v[102:103], v[102:103], v[172:173]
	v_pk_mul_f32 v[32:33], v[32:33], v[166:167]
	v_pk_mul_f32 v[96:97], v[96:97], v[186:187]
	v_pk_mul_f32 v[34:35], v[34:35], v[168:169]
	v_pk_mul_f32 v[98:99], v[98:99], v[188:189]
	v_pk_add_f32 v[36:37], v[36:37], v[100:101]
	v_pk_add_f32 v[38:39], v[38:39], v[102:103]
	v_pk_add_f32 v[32:33], v[32:33], v[96:97]
	v_pk_add_f32 v[34:35], v[34:35], v[98:99]
	v_cvt_pk_bf16_f32 v100, v36, v37
	v_cvt_pk_bf16_f32 v101, v38, v39
	v_cvt_pk_bf16_f32 v102, v32, v33
	v_cvt_pk_bf16_f32 v103, v34, v35
	s_waitcnt vmcnt(6)
	v_lshlrev_b32_e32 v162, 16, v244
	v_and_b32_e32 v163, 0xffff0000, v244
	v_lshlrev_b32_e32 v170, 16, v150
	v_and_b32_e32 v171, 0xffff0000, v150
	v_lshlrev_b32_e32 v164, 16, v245
	v_and_b32_e32 v165, 0xffff0000, v245
	v_lshlrev_b32_e32 v172, 16, v151
	v_and_b32_e32 v173, 0xffff0000, v151
	v_lshlrev_b32_e32 v166, 16, v246
	v_and_b32_e32 v167, 0xffff0000, v246
	v_lshlrev_b32_e32 v186, 16, v152
	v_and_b32_e32 v187, 0xffff0000, v152
	v_lshlrev_b32_e32 v168, 16, v247
	v_and_b32_e32 v169, 0xffff0000, v247
	v_lshlrev_b32_e32 v188, 16, v153
	v_and_b32_e32 v189, 0xffff0000, v153
	v_pk_mul_f32 v[28:29], v[28:29], v[162:163]
	v_pk_mul_f32 v[92:93], v[92:93], v[170:171]
	v_pk_mul_f32 v[30:31], v[30:31], v[164:165]
	v_pk_mul_f32 v[94:95], v[94:95], v[172:173]
	v_pk_mul_f32 v[24:25], v[24:25], v[166:167]
	v_pk_mul_f32 v[88:89], v[88:89], v[186:187]
	v_pk_mul_f32 v[26:27], v[26:27], v[168:169]
	v_pk_mul_f32 v[90:91], v[90:91], v[188:189]
	v_pk_add_f32 v[28:29], v[28:29], v[92:93]
	v_pk_add_f32 v[30:31], v[30:31], v[94:95]
	v_pk_add_f32 v[24:25], v[24:25], v[88:89]
	v_pk_add_f32 v[26:27], v[26:27], v[90:91]
	v_cvt_pk_bf16_f32 v92, v28, v29
	v_cvt_pk_bf16_f32 v93, v30, v31
	v_cvt_pk_bf16_f32 v94, v24, v25
	v_cvt_pk_bf16_f32 v95, v26, v27
	s_waitcnt vmcnt(4)
	v_lshlrev_b32_e32 v162, 16, v154
	v_and_b32_e32 v163, 0xffff0000, v154
	v_lshlrev_b32_e32 v170, 16, v158
	v_and_b32_e32 v171, 0xffff0000, v158
	v_lshlrev_b32_e32 v164, 16, v155
	v_and_b32_e32 v165, 0xffff0000, v155
	v_lshlrev_b32_e32 v172, 16, v159
	v_and_b32_e32 v173, 0xffff0000, v159
	v_lshlrev_b32_e32 v166, 16, v156
	v_and_b32_e32 v167, 0xffff0000, v156
	v_lshlrev_b32_e32 v186, 16, v160
	v_and_b32_e32 v187, 0xffff0000, v160
	v_lshlrev_b32_e32 v168, 16, v157
	v_and_b32_e32 v169, 0xffff0000, v157
	v_lshlrev_b32_e32 v188, 16, v161
	v_and_b32_e32 v189, 0xffff0000, v161
	v_pk_mul_f32 v[20:21], v[20:21], v[162:163]
	v_pk_mul_f32 v[84:85], v[84:85], v[170:171]
	v_pk_mul_f32 v[22:23], v[22:23], v[164:165]
	v_pk_mul_f32 v[86:87], v[86:87], v[172:173]
	v_pk_mul_f32 v[16:17], v[16:17], v[166:167]
	v_pk_mul_f32 v[80:81], v[80:81], v[186:187]
	v_pk_mul_f32 v[18:19], v[18:19], v[168:169]
	v_pk_mul_f32 v[82:83], v[82:83], v[188:189]
	v_pk_add_f32 v[20:21], v[20:21], v[84:85]
	v_pk_add_f32 v[22:23], v[22:23], v[86:87]
	v_pk_add_f32 v[16:17], v[16:17], v[80:81]
	v_pk_add_f32 v[18:19], v[18:19], v[82:83]
	v_cvt_pk_bf16_f32 v84, v20, v21
	v_cvt_pk_bf16_f32 v85, v22, v23
	v_cvt_pk_bf16_f32 v86, v16, v17
	v_cvt_pk_bf16_f32 v87, v18, v19
	s_waitcnt vmcnt(2)
; __device__ __forceinline__ unsigned cvt_pk_bf16(float lo, float hi) { unsigned r; asm volatile("v_cvt_pk_bf16_f32 %0, %1, %2" : "=v"(r) : "v"(lo), "v"(hi)); return r; }
; __device__ __forceinline__ float bflo(unsigned w) { return __uint_as_float(w << 16); }
; __device__ __forceinline__ float bfhi(unsigned w) { return __uint_as_float(w & 0xffff0000u); }
;     __device__ __forceinline__ void operator()(const f32x4 (&acc)[2][2][4][2], const Unit& u, int wr, int wc, int fr, int fq) const {
;     ...
;                 const f32x4 a0 = acc[ai][0][m][0], a1 = acc[ai][0][m][1], b0 = acc[ai][1][m][0], b1 = acc[ai][1][m][1];
;                 u32x4 w;
;                 w.x = cvt_pk_bf16(bflo(ga.x) * a0[0] + bflo(gb.x) * b0[0], bfhi(ga.x) * a0[1] + bfhi(gb.x) * b0[1]);
;                 w.y = cvt_pk_bf16(bflo(ga.y) * a0[2] + bflo(gb.y) * b0[2], bfhi(ga.y) * a0[3] + bfhi(gb.y) * b0[3]);
;                 w.z = cvt_pk_bf16(bflo(ga.z) * a1[0] + bflo(gb.z) * b1[0], bfhi(ga.z) * a1[1] + bfhi(gb.z) * b1[1]);
;                 w.w = cvt_pk_bf16(bflo(ga.w) * a1[2] + bflo(gb.w) * b1[2], bfhi(ga.w) * a1[3] + bfhi(gb.w) * b1[3]);
;                 *(u32x4*)(MRG + (size_t)row * 1024 + col0) = w;
	v_lshlrev_b32_e32 v162, 16, v212
	v_and_b32_e32 v163, 0xffff0000, v212
	v_lshlrev_b32_e32 v170, 16, v216
	v_and_b32_e32 v171, 0xffff0000, v216
	v_lshlrev_b32_e32 v164, 16, v213
	v_and_b32_e32 v165, 0xffff0000, v213
	v_lshlrev_b32_e32 v172, 16, v217
	v_and_b32_e32 v173, 0xffff0000, v217
	v_lshlrev_b32_e32 v166, 16, v214
	v_and_b32_e32 v167, 0xffff0000, v214
	v_lshlrev_b32_e32 v186, 16, v218
	v_and_b32_e32 v187, 0xffff0000, v218
	v_lshlrev_b32_e32 v168, 16, v215
	v_and_b32_e32 v169, 0xffff0000, v215
	v_lshlrev_b32_e32 v188, 16, v219
	v_and_b32_e32 v189, 0xffff0000, v219
	v_pk_mul_f32 v[12:13], v[12:13], v[162:163]
	v_pk_mul_f32 v[76:77], v[76:77], v[170:171]
	v_pk_mul_f32 v[14:15], v[14:15], v[164:165]
	v_pk_mul_f32 v[78:79], v[78:79], v[172:173]
	v_pk_mul_f32 v[8:9], v[8:9], v[166:167]
	v_pk_mul_f32 v[68:69], v[68:69], v[186:187]
	v_pk_mul_f32 v[10:11], v[10:11], v[168:169]
	v_pk_mul_f32 v[70:71], v[70:71], v[188:189]
	v_pk_add_f32 v[12:13], v[12:13], v[76:77]
	v_pk_add_f32 v[14:15], v[14:15], v[78:79]
	v_pk_add_f32 v[8:9], v[8:9], v[68:69]
	v_pk_add_f32 v[10:11], v[10:11], v[70:71]
	v_cvt_pk_bf16_f32 v76, v12, v13
	v_cvt_pk_bf16_f32 v77, v14, v15
	v_cvt_pk_bf16_f32 v78, v8, v9
	v_cvt_pk_bf16_f32 v79, v10, v11
	s_waitcnt vmcnt(0)
	v_lshlrev_b32_e32 v162, 16, v220
	v_and_b32_e32 v163, 0xffff0000, v220
	v_lshlrev_b32_e32 v170, 16, v224
	v_and_b32_e32 v171, 0xffff0000, v224
	v_lshlrev_b32_e32 v164, 16, v221
	v_and_b32_e32 v165, 0xffff0000, v221
	v_lshlrev_b32_e32 v172, 16, v225
	v_and_b32_e32 v173, 0xffff0000, v225
	v_lshlrev_b32_e32 v166, 16, v222
	v_and_b32_e32 v167, 0xffff0000, v222
	v_lshlrev_b32_e32 v186, 16, v226
	v_and_b32_e32 v187, 0xffff0000, v226
	v_lshlrev_b32_e32 v168, 16, v223
	v_and_b32_e32 v169, 0xffff0000, v223
	v_lshlrev_b32_e32 v188, 16, v227
	v_and_b32_e32 v189, 0xffff0000, v227
	v_pk_mul_f32 v[4:5], v[4:5], v[162:163]
	v_pk_mul_f32 v[60:61], v[60:61], v[170:171]
	v_pk_mul_f32 v[6:7], v[6:7], v[164:165]
	v_pk_mul_f32 v[62:63], v[62:63], v[172:173]
	v_pk_mul_f32 v[0:1], v[0:1], v[166:167]
	v_pk_mul_f32 v[56:57], v[56:57], v[186:187]
	v_pk_mul_f32 v[2:3], v[2:3], v[168:169]
	v_pk_mul_f32 v[58:59], v[58:59], v[188:189]
	v_pk_add_f32 v[4:5], v[4:5], v[60:61]
	v_pk_add_f32 v[6:7], v[6:7], v[62:63]
	v_pk_add_f32 v[0:1], v[0:1], v[56:57]
	v_pk_add_f32 v[2:3], v[2:3], v[58:59]
	v_cvt_pk_bf16_f32 v60, v4, v5
	v_cvt_pk_bf16_f32 v61, v6, v7
	v_cvt_pk_bf16_f32 v62, v0, v1
	v_cvt_pk_bf16_f32 v63, v2, v3
	global_store_dwordx4 v[192:193], v[124:127], off
	s_mov_b64 s[6:7], 0x8000
	v_lshl_add_u64 v[248:249], v[192:193], 0, s[6:7]
	global_store_dwordx4 v[248:249], v[116:119], off
	s_mov_b64 s[6:7], 0x10000
	v_lshl_add_u64 v[198:199], v[192:193], 0, s[6:7]
	global_store_dwordx4 v[198:199], v[108:111], off
	s_mov_b64 s[6:7], 0x18000
	v_lshl_add_u64 v[248:249], v[192:193], 0, s[6:7]
	global_store_dwordx4 v[248:249], v[100:103], off
	s_mov_b64 s[6:7], 0x40000
	v_lshl_add_u64 v[198:199], v[192:193], 0, s[6:7]
	global_store_dwordx4 v[198:199], v[92:95], off
	s_mov_b64 s[6:7], 0x48000
	v_lshl_add_u64 v[248:249], v[192:193], 0, s[6:7]
	global_store_dwordx4 v[248:249], v[84:87], off
	s_mov_b64 s[6:7], 0x50000
	v_lshl_add_u64 v[198:199], v[192:193], 0, s[6:7]
	global_store_dwordx4 v[198:199], v[76:79], off
	s_mov_b64 s[6:7], 0x58000
	v_lshl_add_u64 v[248:249], v[192:193], 0, s[6:7]
	global_store_dwordx4 v[248:249], v[60:63], off
	s_cbranch_vccnz .LBB0_1045
	s_andn2_b64 vcc, exec, s[10:11]
	s_cbranch_vccnz .LBB0_1044
	s_barrier
	s_branch .LBB0_1044

; __device__ __forceinline__ unsigned cvt_pk_bf16(float lo, float hi) { unsigned r; asm volatile("v_cvt_pk_bf16_f32 %0, %1, %2" : "=v"(r) : "v"(lo), "v"(hi)); return r; }
; __device__ __forceinline__ float bflo(unsigned w) { return __uint_as_float(w << 16); }
; __device__ __forceinline__ float bfhi(unsigned w) { return __uint_as_float(w & 0xffff0000u); }
;     __device__ __forceinline__ void operator()(const f32x4 (&acc)[2][2][4][2], const Unit& u, int wr, int wc, int fr, int fq) const {
;         const int row0 = u.pm * BM + wr * 64 + fr, col0 = u.pn * HALF + wc * 32 + 8 * fq;
; #pragma unroll
;         for (int ai = 0; ai < 2; ++ai)
; #pragma unroll
;             for (int m = 0; m < 4; ++m) {
;                 const int row = row0 + ai * HALF + m * 16;
;                 const u32x4 ga = *(const u32x4*)(GT + (size_t)row * 2048 + col0), gb = *(const u32x4*)(GT + (size_t)row * 2048 + 1024 + col0);
;                 const f32x4 a0 = acc[ai][0][m][0], a1 = acc[ai][0][m][1], b0 = acc[ai][1][m][0], b1 = acc[ai][1][m][1];
;                 u32x4 w;
;                 w.x = cvt_pk_bf16(bflo(ga.x) * a0[0] + bflo(gb.x) * b0[0], bfhi(ga.x) * a0[1] + bfhi(gb.x) * b0[1]);
;                 w.y = cvt_pk_bf16(bflo(ga.y) * a0[2] + bflo(gb.y) * b0[2], bfhi(ga.y) * a0[3] + bfhi(gb.y) * b0[3]);
;                 w.z = cvt_pk_bf16(bflo(ga.z) * a1[0] + bflo(gb.z) * b1[0], bfhi(ga.z) * a1[1] + bfhi(gb.z) * b1[1]);
;                 w.w = cvt_pk_bf16(bflo(ga.w) * a1[2] + bflo(gb.w) * b1[2], bfhi(ga.w) * a1[3] + bfhi(gb.w) * b1[3]);
.LBB0_2261:
	s_andn2_b64 vcc, exec, s[6:7]
	s_mov_b64 s[6:7], -1
	v_lshl_add_u32 v196, s66, 8, v144
	v_lshl_or_b32 v194, s90, 7, v147
	v_ashrrev_i32_e32 v197, 31, v196
	v_ashrrev_i32_e32 v195, 31, v194
	v_lshlrev_b64 v[190:191], 12, v[196:197]
	v_lshlrev_b64 v[194:195], 1, v[194:195]
	v_lshl_add_u64 v[190:191], s[10:11], 0, v[190:191]
	v_lshlrev_b64 v[192:193], 11, v[196:197]
	v_lshl_add_u64 v[190:191], v[190:191], 0, v[194:195]
	v_lshl_add_u64 v[192:193], s[12:13], 0, v[192:193]
	v_lshl_add_u64 v[192:193], v[192:193], 0, v[194:195]
	global_load_dwordx4 v[212:215], v[190:191], off
	global_load_dwordx4 v[216:219], v[190:191], off offset:2048
	s_mov_b64 s[68:69], 0x10000
	v_lshl_add_u64 v[198:199], v[190:191], 0, s[68:69]
	global_load_dwordx4 v[220:223], v[198:199], off
	global_load_dwordx4 v[224:227], v[198:199], off offset:2048
	s_mov_b64 s[68:69], 0x20000
	v_lshl_add_u64 v[248:249], v[190:191], 0, s[68:69]
	global_load_dwordx4 v[228:231], v[248:249], off
	global_load_dwordx4 v[232:235], v[248:249], off offset:2048
	s_mov_b64 s[68:69], 0x30000
	v_lshl_add_u64 v[198:199], v[190:191], 0, s[68:69]
	global_load_dwordx4 v[236:239], v[198:199], off
	global_load_dwordx4 v[240:243], v[198:199], off offset:2048
	s_mov_b64 s[68:69], 0x80000
	v_lshl_add_u64 v[248:249], v[190:191], 0, s[68:69]
	global_load_dwordx4 v[244:247], v[248:249], off
	global_load_dwordx4 v[150:153], v[248:249], off offset:2048
	s_mov_b64 s[68:69], 0x90000
	v_lshl_add_u64 v[198:199], v[190:191], 0, s[68:69]
	global_load_dwordx4 v[154:157], v[198:199], off
	global_load_dwordx4 v[158:161], v[198:199], off offset:2048
	s_waitcnt vmcnt(10)
	v_lshlrev_b32_e32 v162, 16, v212
	v_and_b32_e32 v163, 0xffff0000, v212
	v_lshlrev_b32_e32 v170, 16, v216
	v_and_b32_e32 v171, 0xffff0000, v216
	v_lshlrev_b32_e32 v164, 16, v213
	v_and_b32_e32 v165, 0xffff0000, v213
	v_lshlrev_b32_e32 v172, 16, v217
	v_and_b32_e32 v173, 0xffff0000, v217
	v_lshlrev_b32_e32 v166, 16, v214
	v_and_b32_e32 v167, 0xffff0000, v214
	v_lshlrev_b32_e32 v186, 16, v218
	v_and_b32_e32 v187, 0xffff0000, v218
	v_lshlrev_b32_e32 v168, 16, v215
	v_and_b32_e32 v169, 0xffff0000, v215
	v_lshlrev_b32_e32 v188, 16, v219
	v_and_b32_e32 v189, 0xffff0000, v219
	s_mov_b64 s[68:69], 0xa0000
	v_lshl_add_u64 v[248:249], v[190:191], 0, s[68:69]
	global_load_dwordx4 v[212:215], v[248:249], off
	global_load_dwordx4 v[216:219], v[248:249], off offset:2048
	v_pk_mul_f32 v[72:73], v[72:73], v[162:163]
	v_pk_mul_f32 v[124:125], v[124:125], v[170:171]
	v_pk_mul_f32 v[74:75], v[74:75], v[164:165]
	v_pk_mul_f32 v[126:127], v[126:127], v[172:173]
	v_pk_mul_f32 v[64:65], v[64:65], v[166:167]
	v_pk_mul_f32 v[120:121], v[120:121], v[186:187]
	v_pk_mul_f32 v[66:67], v[66:67], v[168:169]
	v_pk_mul_f32 v[122:123], v[122:123], v[188:189]
	v_pk_add_f32 v[72:73], v[72:73], v[124:125]
	v_pk_add_f32 v[74:75], v[74:75], v[126:127]
	v_pk_add_f32 v[64:65], v[64:65], v[120:121]
	v_pk_add_f32 v[66:67], v[66:67], v[122:123]
	v_cvt_pk_bf16_f32 v124, v72, v73
	v_cvt_pk_bf16_f32 v125, v74, v75
	v_cvt_pk_bf16_f32 v126, v64, v65
	v_cvt_pk_bf16_f32 v127, v66, v67
	s_waitcnt vmcnt(10)
	v_lshlrev_b32_e32 v162, 16, v220
	v_and_b32_e32 v163, 0xffff0000, v220
	v_lshlrev_b32_e32 v170, 16, v224
	v_and_b32_e32 v171, 0xffff0000, v224
	v_lshlrev_b32_e32 v164, 16, v221
	v_and_b32_e32 v165, 0xffff0000, v221
	v_lshlrev_b32_e32 v172, 16, v225
	v_and_b32_e32 v173, 0xffff0000, v225
	v_lshlrev_b32_e32 v166, 16, v222
	v_and_b32_e32 v167, 0xffff0000, v222
	v_lshlrev_b32_e32 v186, 16, v226
	v_and_b32_e32 v187, 0xffff0000, v226
	v_lshlrev_b32_e32 v168, 16, v223
	v_and_b32_e32 v169, 0xffff0000, v223
	v_lshlrev_b32_e32 v188, 16, v227
	v_and_b32_e32 v189, 0xffff0000, v227
	s_mov_b64 s[68:69], 0xb0000
	v_lshl_add_u64 v[198:199], v[190:191], 0, s[68:69]
	global_load_dwordx4 v[220:223], v[198:199], off
	global_load_dwordx4 v[224:227], v[198:199], off offset:2048
	v_pk_mul_f32 v[52:53], v[52:53], v[162:163]
	v_pk_mul_f32 v[116:117], v[116:117], v[170:171]
	v_pk_mul_f32 v[54:55], v[54:55], v[164:165]
	v_pk_mul_f32 v[118:119], v[118:119], v[172:173]
	v_pk_mul_f32 v[48:49], v[48:49], v[166:167]
	v_pk_mul_f32 v[112:113], v[112:113], v[186:187]
	v_pk_mul_f32 v[50:51], v[50:51], v[168:169]
	v_pk_mul_f32 v[114:115], v[114:115], v[188:189]
	v_pk_add_f32 v[52:53], v[52:53], v[116:117]
	v_pk_add_f32 v[54:55], v[54:55], v[118:119]
	v_pk_add_f32 v[48:49], v[48:49], v[112:113]
	v_pk_add_f32 v[50:51], v[50:51], v[114:115]
	v_cvt_pk_bf16_f32 v116, v52, v53
	v_cvt_pk_bf16_f32 v117, v54, v55
	v_cvt_pk_bf16_f32 v118, v48, v49
	v_cvt_pk_bf16_f32 v119, v50, v51
	s_waitcnt vmcnt(10)
	v_lshlrev_b32_e32 v162, 16, v228
	v_and_b32_e32 v163, 0xffff0000, v228
	v_lshlrev_b32_e32 v170, 16, v232
	v_and_b32_e32 v171, 0xffff0000, v232
	v_lshlrev_b32_e32 v164, 16, v229
	v_and_b32_e32 v165, 0xffff0000, v229
	v_lshlrev_b32_e32 v172, 16, v233
	v_and_b32_e32 v173, 0xffff0000, v233
	v_lshlrev_b32_e32 v166, 16, v230
	v_and_b32_e32 v167, 0xffff0000, v230
	v_lshlrev_b32_e32 v186, 16, v234
	v_and_b32_e32 v187, 0xffff0000, v234
	v_lshlrev_b32_e32 v168, 16, v231
	v_and_b32_e32 v169, 0xffff0000, v231
	v_lshlrev_b32_e32 v188, 16, v235
	v_and_b32_e32 v189, 0xffff0000, v235
	v_pk_mul_f32 v[44:45], v[44:45], v[162:163]
	v_pk_mul_f32 v[108:109], v[108:109], v[170:171]
	v_pk_mul_f32 v[46:47], v[46:47], v[164:165]
	v_pk_mul_f32 v[110:111], v[110:111], v[172:173]
	v_pk_mul_f32 v[40:41], v[40:41], v[166:167]
	v_pk_mul_f32 v[104:105], v[104:105], v[186:187]
	v_pk_mul_f32 v[42:43], v[42:43], v[168:169]
	v_pk_mul_f32 v[106:107], v[106:107], v[188:189]
	v_pk_add_f32 v[44:45], v[44:45], v[108:109]
	v_pk_add_f32 v[46:47], v[46:47], v[110:111]
	v_pk_add_f32 v[40:41], v[40:41], v[104:105]
	v_pk_add_f32 v[42:43], v[42:43], v[106:107]
	v_cvt_pk_bf16_f32 v108, v44, v45
	v_cvt_pk_bf16_f32 v109, v46, v47
	v_cvt_pk_bf16_f32 v110, v40, v41
	v_cvt_pk_bf16_f32 v111, v42, v43
	s_waitcnt vmcnt(8)
; __device__ __forceinline__ unsigned cvt_pk_bf16(float lo, float hi) { unsigned r; asm volatile("v_cvt_pk_bf16_f32 %0, %1, %2" : "=v"(r) : "v"(lo), "v"(hi)); return r; }
; __device__ __forceinline__ float bflo(unsigned w) { return __uint_as_float(w << 16); }
; __device__ __forceinline__ float bfhi(unsigned w) { return __uint_as_float(w & 0xffff0000u); }
;     __device__ __forceinline__ void operator()(const f32x4 (&acc)[2][2][4][2], const Unit& u, int wr, int wc, int fr, int fq) const {
;     ...
;                 const f32x4 a0 = acc[ai][0][m][0], a1 = acc[ai][0][m][1], b0 = acc[ai][1][m][0], b1 = acc[ai][1][m][1];
;                 u32x4 w;
;                 w.x = cvt_pk_bf16(bflo(ga.x) * a0[0] + bflo(gb.x) * b0[0], bfhi(ga.x) * a0[1] + bfhi(gb.x) * b0[1]);
;                 w.y = cvt_pk_bf16(bflo(ga.y) * a0[2] + bflo(gb.y) * b0[2], bfhi(ga.y) * a0[3] + bfhi(gb.y) * b0[3]);
;                 w.z = cvt_pk_bf16(bflo(ga.z) * a1[0] + bflo(gb.z) * b1[0], bfhi(ga.z) * a1[1] + bfhi(gb.z) * b1[1]);
;                 w.w = cvt_pk_bf16(bflo(ga.w) * a1[2] + bflo(gb.w) * b1[2], bfhi(ga.w) * a1[3] + bfhi(gb.w) * b1[3]);
	v_lshlrev_b32_e32 v162, 16, v236
	v_and_b32_e32 v163, 0xffff0000, v236
	v_lshlrev_b32_e32 v170, 16, v240
	v_and_b32_e32 v171, 0xffff0000, v240
	v_lshlrev_b32_e32 v164, 16, v237
	v_and_b32_e32 v165, 0xffff0000, v237
	v_lshlrev_b32_e32 v172, 16, v241
	v_and_b32_e32 v173, 0xffff0000, v241
	v_lshlrev_b32_e32 v166, 16, v238
	v_and_b32_e32 v167, 0xffff0000, v238
	v_lshlrev_b32_e32 v186, 16, v242
	v_and_b32_e32 v187, 0xffff0000, v242
	v_lshlrev_b32_e32 v168, 16, v239
	v_and_b32_e32 v169, 0xffff0000, v239
	v_lshlrev_b32_e32 v188, 16, v243
	v_and_b32_e32 v189, 0xffff0000, v243
	v_pk_mul_f32 v[36:37], v[36:37], v[162:163]
	v_pk_mul_f32 v[100:101], v[100:101], v[170:171]
	v_pk_mul_f32 v[38:39], v[38:39], v[164:165]
	v_pk_mul_f32 v[102:103], v[102:103], v[172:173]
	v_pk_mul_f32 v[32:33], v[32:33], v[166:167]
	v_pk_mul_f32 v[96:97], v[96:97], v[186:187]
	v_pk_mul_f32 v[34:35], v[34:35], v[168:169]
	v_pk_mul_f32 v[98:99], v[98:99], v[188:189]
	v_pk_add_f32 v[36:37], v[36:37], v[100:101]
	v_pk_add_f32 v[38:39], v[38:39], v[102:103]
	v_pk_add_f32 v[32:33], v[32:33], v[96:97]
	v_pk_add_f32 v[34:35], v[34:35], v[98:99]
	v_cvt_pk_bf16_f32 v100, v36, v37
	v_cvt_pk_bf16_f32 v101, v38, v39
	v_cvt_pk_bf16_f32 v102, v32, v33
	v_cvt_pk_bf16_f32 v103, v34, v35
	s_waitcnt vmcnt(6)
	v_lshlrev_b32_e32 v162, 16, v244
	v_and_b32_e32 v163, 0xffff0000, v244
	v_lshlrev_b32_e32 v170, 16, v150
	v_and_b32_e32 v171, 0xffff0000, v150
	v_lshlrev_b32_e32 v164, 16, v245
	v_and_b32_e32 v165, 0xffff0000, v245
	v_lshlrev_b32_e32 v172, 16, v151
	v_and_b32_e32 v173, 0xffff0000, v151
	v_lshlrev_b32_e32 v166, 16, v246
	v_and_b32_e32 v167, 0xffff0000, v246
	v_lshlrev_b32_e32 v186, 16, v152
	v_and_b32_e32 v187, 0xffff0000, v152
	v_lshlrev_b32_e32 v168, 16, v247
	v_and_b32_e32 v169, 0xffff0000, v247
	v_lshlrev_b32_e32 v188, 16, v153
	v_and_b32_e32 v189, 0xffff0000, v153
	v_pk_mul_f32 v[28:29], v[28:29], v[162:163]
	v_pk_mul_f32 v[92:93], v[92:93], v[170:171]
	v_pk_mul_f32 v[30:31], v[30:31], v[164:165]
	v_pk_mul_f32 v[94:95], v[94:95], v[172:173]
	v_pk_mul_f32 v[24:25], v[24:25], v[166:167]
	v_pk_mul_f32 v[88:89], v[88:89], v[186:187]
	v_pk_mul_f32 v[26:27], v[26:27], v[168:169]
	v_pk_mul_f32 v[90:91], v[90:91], v[188:189]
	v_pk_add_f32 v[28:29], v[28:29], v[92:93]
	v_pk_add_f32 v[30:31], v[30:31], v[94:95]
	v_pk_add_f32 v[24:25], v[24:25], v[88:89]
	v_pk_add_f32 v[26:27], v[26:27], v[90:91]
	v_cvt_pk_bf16_f32 v92, v28, v29
	v_cvt_pk_bf16_f32 v93, v30, v31
	v_cvt_pk_bf16_f32 v94, v24, v25
	v_cvt_pk_bf16_f32 v95, v26, v27
	s_waitcnt vmcnt(4)
	v_lshlrev_b32_e32 v162, 16, v154
	v_and_b32_e32 v163, 0xffff0000, v154
	v_lshlrev_b32_e32 v170, 16, v158
	v_and_b32_e32 v171, 0xffff0000, v158
	v_lshlrev_b32_e32 v164, 16, v155
	v_and_b32_e32 v165, 0xffff0000, v155
	v_lshlrev_b32_e32 v172, 16, v159
	v_and_b32_e32 v173, 0xffff0000, v159
	v_lshlrev_b32_e32 v166, 16, v156
	v_and_b32_e32 v167, 0xffff0000, v156
	v_lshlrev_b32_e32 v186, 16, v160
	v_and_b32_e32 v187, 0xffff0000, v160
	v_lshlrev_b32_e32 v168, 16, v157
	v_and_b32_e32 v169, 0xffff0000, v157
	v_lshlrev_b32_e32 v188, 16, v161
	v_and_b32_e32 v189, 0xffff0000, v161
	v_pk_mul_f32 v[20:21], v[20:21], v[162:163]
	v_pk_mul_f32 v[84:85], v[84:85], v[170:171]
	v_pk_mul_f32 v[22:23], v[22:23], v[164:165]
	v_pk_mul_f32 v[86:87], v[86:87], v[172:173]
	v_pk_mul_f32 v[16:17], v[16:17], v[166:167]
	v_pk_mul_f32 v[80:81], v[80:81], v[186:187]
	v_pk_mul_f32 v[18:19], v[18:19], v[168:169]
	v_pk_mul_f32 v[82:83], v[82:83], v[188:189]
	v_pk_add_f32 v[20:21], v[20:21], v[84:85]
	v_pk_add_f32 v[22:23], v[22:23], v[86:87]
	v_pk_add_f32 v[16:17], v[16:17], v[80:81]
	v_pk_add_f32 v[18:19], v[18:19], v[82:83]
	v_cvt_pk_bf16_f32 v84, v20, v21
	v_cvt_pk_bf16_f32 v85, v22, v23
	v_cvt_pk_bf16_f32 v86, v16, v17
	v_cvt_pk_bf16_f32 v87, v18, v19
	s_waitcnt vmcnt(2)
; __device__ __forceinline__ unsigned cvt_pk_bf16(float lo, float hi) { unsigned r; asm volatile("v_cvt_pk_bf16_f32 %0, %1, %2" : "=v"(r) : "v"(lo), "v"(hi)); return r; }
; __device__ __forceinline__ float bflo(unsigned w) { return __uint_as_float(w << 16); }
; __device__ __forceinline__ float bfhi(unsigned w) { return __uint_as_float(w & 0xffff0000u); }
;     __device__ __forceinline__ void operator()(const f32x4 (&acc)[2][2][4][2], const Unit& u, int wr, int wc, int fr, int fq) const {
;     ...
;                 const f32x4 a0 = acc[ai][0][m][0], a1 = acc[ai][0][m][1], b0 = acc[ai][1][m][0], b1 = acc[ai][1][m][1];
;                 u32x4 w;
;                 w.x = cvt_pk_bf16(bflo(ga.x) * a0[0] + bflo(gb.x) * b0[0], bfhi(ga.x) * a0[1] + bfhi(gb.x) * b0[1]);
;                 w.y = cvt_pk_bf16(bflo(ga.y) * a0[2] + bflo(gb.y) * b0[2], bfhi(ga.y) * a0[3] + bfhi(gb.y) * b0[3]);
;                 w.z = cvt_pk_bf16(bflo(ga.z) * a1[0] + bflo(gb.z) * b1[0], bfhi(ga.z) * a1[1] + bfhi(gb.z) * b1[1]);
;                 w.w = cvt_pk_bf16(bflo(ga.w) * a1[2] + bflo(gb.w) * b1[2], bfhi(ga.w) * a1[3] + bfhi(gb.w) * b1[3]);
;                 *(u32x4*)(MRG + (size_t)row * 1024 + col0) = w;
	v_lshlrev_b32_e32 v162, 16, v212
	v_and_b32_e32 v163, 0xffff0000, v212
	v_lshlrev_b32_e32 v170, 16, v216
	v_and_b32_e32 v171, 0xffff0000, v216
	v_lshlrev_b32_e32 v164, 16, v213
	v_and_b32_e32 v165, 0xffff0000, v213
	v_lshlrev_b32_e32 v172, 16, v217
	v_and_b32_e32 v173, 0xffff0000, v217
	v_lshlrev_b32_e32 v166, 16, v214
	v_and_b32_e32 v167, 0xffff0000, v214
	v_lshlrev_b32_e32 v186, 16, v218
	v_and_b32_e32 v187, 0xffff0000, v218
	v_lshlrev_b32_e32 v168, 16, v215
	v_and_b32_e32 v169, 0xffff0000, v215
	v_lshlrev_b32_e32 v188, 16, v219
	v_and_b32_e32 v189, 0xffff0000, v219
	v_pk_mul_f32 v[12:13], v[12:13], v[162:163]
	v_pk_mul_f32 v[76:77], v[76:77], v[170:171]
	v_pk_mul_f32 v[14:15], v[14:15], v[164:165]
	v_pk_mul_f32 v[78:79], v[78:79], v[172:173]
	v_pk_mul_f32 v[8:9], v[8:9], v[166:167]
	v_pk_mul_f32 v[68:69], v[68:69], v[186:187]
	v_pk_mul_f32 v[10:11], v[10:11], v[168:169]
	v_pk_mul_f32 v[70:71], v[70:71], v[188:189]
	v_pk_add_f32 v[12:13], v[12:13], v[76:77]
	v_pk_add_f32 v[14:15], v[14:15], v[78:79]
	v_pk_add_f32 v[8:9], v[8:9], v[68:69]
	v_pk_add_f32 v[10:11], v[10:11], v[70:71]
	v_cvt_pk_bf16_f32 v76, v12, v13
	v_cvt_pk_bf16_f32 v77, v14, v15
	v_cvt_pk_bf16_f32 v78, v8, v9
	v_cvt_pk_bf16_f32 v79, v10, v11
	s_waitcnt vmcnt(0)
	v_lshlrev_b32_e32 v162, 16, v220
	v_and_b32_e32 v163, 0xffff0000, v220
	v_lshlrev_b32_e32 v170, 16, v224
	v_and_b32_e32 v171, 0xffff0000, v224
	v_lshlrev_b32_e32 v164, 16, v221
	v_and_b32_e32 v165, 0xffff0000, v221
	v_lshlrev_b32_e32 v172, 16, v225
	v_and_b32_e32 v173, 0xffff0000, v225
	v_lshlrev_b32_e32 v166, 16, v222
	v_and_b32_e32 v167, 0xffff0000, v222
	v_lshlrev_b32_e32 v186, 16, v226
	v_and_b32_e32 v187, 0xffff0000, v226
	v_lshlrev_b32_e32 v168, 16, v223
	v_and_b32_e32 v169, 0xffff0000, v223
	v_lshlrev_b32_e32 v188, 16, v227
	v_and_b32_e32 v189, 0xffff0000, v227
	v_pk_mul_f32 v[4:5], v[4:5], v[162:163]
	v_pk_mul_f32 v[60:61], v[60:61], v[170:171]
	v_pk_mul_f32 v[6:7], v[6:7], v[164:165]
	v_pk_mul_f32 v[62:63], v[62:63], v[172:173]
	v_pk_mul_f32 v[0:1], v[0:1], v[166:167]
	v_pk_mul_f32 v[56:57], v[56:57], v[186:187]
	v_pk_mul_f32 v[2:3], v[2:3], v[168:169]
	v_pk_mul_f32 v[58:59], v[58:59], v[188:189]
	v_pk_add_f32 v[4:5], v[4:5], v[60:61]
	v_pk_add_f32 v[6:7], v[6:7], v[62:63]
	v_pk_add_f32 v[0:1], v[0:1], v[56:57]
	v_pk_add_f32 v[2:3], v[2:3], v[58:59]
	v_cvt_pk_bf16_f32 v60, v4, v5
	v_cvt_pk_bf16_f32 v61, v6, v7
	v_cvt_pk_bf16_f32 v62, v0, v1
	v_cvt_pk_bf16_f32 v63, v2, v3
	global_store_dwordx4 v[192:193], v[124:127], off
	s_mov_b64 s[68:69], 0x8000
	v_lshl_add_u64 v[248:249], v[192:193], 0, s[68:69]
	global_store_dwordx4 v[248:249], v[116:119], off
	s_mov_b64 s[68:69], 0x10000
	v_lshl_add_u64 v[198:199], v[192:193], 0, s[68:69]
	global_store_dwordx4 v[198:199], v[108:111], off
	s_mov_b64 s[68:69], 0x18000
	v_lshl_add_u64 v[248:249], v[192:193], 0, s[68:69]
	global_store_dwordx4 v[248:249], v[100:103], off
	s_mov_b64 s[68:69], 0x40000
	v_lshl_add_u64 v[198:199], v[192:193], 0, s[68:69]
	global_store_dwordx4 v[198:199], v[92:95], off
	s_mov_b64 s[68:69], 0x48000
	v_lshl_add_u64 v[248:249], v[192:193], 0, s[68:69]
	global_store_dwordx4 v[248:249], v[84:87], off
	s_mov_b64 s[68:69], 0x50000
	v_lshl_add_u64 v[198:199], v[192:193], 0, s[68:69]
	global_store_dwordx4 v[198:199], v[76:79], off
	s_mov_b64 s[68:69], 0x58000
	v_lshl_add_u64 v[248:249], v[192:193], 0, s[68:69]
	global_store_dwordx4 v[248:249], v[60:63], off
	s_cbranch_vccnz .LBB0_2256
	s_andn2_b64 vcc, exec, s[8:9]
	s_cbranch_vccnz .LBB0_2255
	s_barrier
	s_branch .LBB0_2255
